# v44 + one static s_setprio 1 for waves 4-7 at kernel entry (no per-segment flips)
# baseline (speedup 1.0000x reference)
_Z10fwd_kernel4Args:
	v_lshrrev_b32_e32 v233, 8, v0
	s_nop 0
	v_readfirstlane_b32 s100, v233
	s_cmp_eq_u32 s100, 0
	s_cbranch_scc1 .Lsprio_skip
	s_setprio 1
.Lsprio_skip:
	s_load_dword s96, s[0:1], 0xf8
	s_mov_b32 s84, s2
	s_add_u32 s2, s0, 0xf8
	s_addc_u32 s3, s1, 0
	s_mov_b32 s8, s84
	v_writelane_b32 v251, s2, 0
	s_nop 1
	v_writelane_b32 v251, s3, 1
	s_waitcnt lgkmcnt(0)
	s_and_b32 s2, s96, 7
	s_cmp_lg_u32 s2, 0
	s_cbranch_scc1 .LBB0_2
	s_ashr_i32 s3, s84, 31
	s_lshr_b32 s3, s3, 29
	s_add_i32 s3, s84, s3
	s_and_b32 s4, s3, -8
	s_ashr_i32 s2, s96, 3
	s_sub_i32 s4, s84, s4
	s_mul_i32 s2, s2, s4
	s_ashr_i32 s3, s3, 3
	s_add_i32 s8, s2, s3
